# v55 + scan step A2: nine f16->f32 unpack pairs + v_pk_fma_f32(x,y,0) replaced by v_fma_mix_f32 pairs (27 -> 18 instructions per wave), nops/waits regenerated
# speedup vs baseline: 1.0089x; 1.0088x over previous
.LBB0_565:
	v_cndmask_b32_e64 v8, 0, 1, s[34:35]
	v_cmp_ne_u32_e64 s[24:25], 1, v8
	s_andn2_b64 vcc, exec, s[34:35]
	s_cbranch_vccnz .LBB0_573
	ds_read_b128 v[20:23], v226 offset:1536
	ds_read_b128 v[24:27], v226 offset:1792
	ds_read_b128 v[28:31], v226 offset:1600
	ds_read_b128 v[32:35], v226 offset:1856
	ds_read_b64 v[36:37], v115 offset:56320
	ds_read_b64 v[38:39], v116 offset:56320
	ds_read_b64 v[40:41], v227
	ds_read_b64 v[42:43], v228
	ds_read2_b64 v[82:85], v229 offset1:4
	ds_read2_b64 v[158:161], v230 offset1:4
	s_waitcnt lgkmcnt(1)
	v_mfma_f32_16x16x32_f16 v[20:23], v[82:85], v[36:39], v[20:23]
	ds_read2_b64 v[82:85], v231 offset1:4
	s_waitcnt lgkmcnt(1)
	v_mfma_f32_16x16x32_f16 v[24:27], v[158:161], v[40:43], v[24:27]
	ds_read2_b64 v[158:161], v232 offset1:4
	s_add_i32 s38, 0, 0x14800
	s_waitcnt lgkmcnt(1)
	v_mfma_f32_16x16x32_f16 v[28:31], v[82:85], v[36:39], v[28:31]
	ds_read_b64 v[36:37], v119 offset:56320
	ds_read_b64 v[38:39], v120 offset:56320
	s_waitcnt lgkmcnt(2)
	v_mfma_f32_16x16x32_f16 v[32:35], v[158:161], v[40:43], v[32:35]
	ds_read_b64 v[40:41], v233
	ds_read_b64 v[42:43], v234
	ds_read2_b64 v[82:85], v235 offset1:4
	ds_read2_b64 v[158:161], v236 offset1:4
	s_waitcnt lgkmcnt(1)
	v_mfma_f32_16x16x32_f16 v[82:85], v[82:85], v[36:39], v[20:23]
	s_nop 2
	ds_read2_b64 v[20:23], v237 offset1:4
	ds_read2_b64 v[162:165], v238 offset1:4
	s_waitcnt lgkmcnt(2)
	v_mfma_f32_16x16x32_f16 v[158:161], v[158:161], v[40:43], v[24:27]
	ds_read2st64_b32 v[8:9], v239 offset1:1
	s_waitcnt lgkmcnt(2)
	v_mfma_f32_16x16x32_f16 v[24:27], v[20:23], v[36:39], v[28:31]
	v_exp_f32_e32 v36, v82
	s_nop 3
	v_exp_f32_e32 v37, v158
	s_waitcnt lgkmcnt(0)
	v_add_f32_e32 v8, v8, v9
	v_mfma_f32_16x16x32_f16 v[20:23], v[162:165], v[40:43], v[32:35]
	v_fmamk_f32 v36, v36, 0xbf92477c, v147
	v_rcp_f32_e32 v36, v36
	v_add_f32_e32 v37, 1.0, v37
	v_rcp_f32_e32 v86, v37
	s_nop 0
	v_add_f32_dpp v37, v36, v36 row_shr:1 row_mask:0xf bank_mask:0xf bound_ctrl:1
	v_lshlrev_b32_e32 v9, 2, v240
	v_or_b32_e32 v157, 60, v9
	v_add_f32_dpp v37, v37, v37 row_shr:2 row_mask:0xf bank_mask:0xf bound_ctrl:1
	v_add_u32_e32 v32, s38, v123
	ds_read_b128 v[28:31], v32 offset:1280
	ds_read_b128 v[32:35], v32 offset:4864
	v_add_f32_dpp v37, v37, v37 row_shr:4 row_mask:0xf bank_mask:0xf bound_ctrl:1
	s_nop 1
	v_add_f32_dpp v82, v37, v37 row_shr:8 row_mask:0xf bank_mask:0xf bound_ctrl:1
	v_sub_f32_e32 v162, v82, v36
	v_exp_f32_e32 v36, v83
	v_exp_f32_e32 v37, v159
	ds_bpermute_b32 v40, v9, v82 offset:28
	v_max_f32_e32 v8, 0x179abe15, v8
	v_fmamk_f32 v36, v36, 0xbf92477c, v147
	v_rcp_f32_e32 v36, v36
	v_add_f32_e32 v37, 1.0, v37
	v_rcp_f32_e32 v87, v37
	v_rsq_f32_e32 v8, v8
	v_add_f32_dpp v37, v36, v36 row_shr:1 row_mask:0xf bank_mask:0xf bound_ctrl:1
	s_waitcnt lgkmcnt(1)
	v_pk_fma_f32 v[28:29], v[86:87], v[28:29], v[32:33]
	v_add_f32_dpp v37, v37, v37 row_shr:2 row_mask:0xf bank_mask:0xf bound_ctrl:1
	s_nop 1
	v_add_f32_dpp v37, v37, v37 row_shr:4 row_mask:0xf bank_mask:0xf bound_ctrl:1
	s_nop 1
	v_add_f32_dpp v83, v37, v37 row_shr:8 row_mask:0xf bank_mask:0xf bound_ctrl:1
	v_sub_f32_e32 v163, v83, v36
	v_exp_f32_e32 v36, v84
	v_exp_f32_e32 v37, v160
	ds_bpermute_b32 v41, v9, v83 offset:28
	s_waitcnt lgkmcnt(1)
	v_sub_f32_e32 v84, v162, v40
	v_fmamk_f32 v36, v36, 0xbf92477c, v147
	v_rcp_f32_e32 v36, v36
	v_add_f32_e32 v37, 1.0, v37
	v_rcp_f32_e32 v158, v37
	v_exp_f32_e32 v160, v84
	v_add_f32_dpp v37, v36, v36 row_shr:1 row_mask:0xf bank_mask:0xf bound_ctrl:1
	s_nop 1
	v_add_f32_dpp v37, v37, v37 row_shr:2 row_mask:0xf bank_mask:0xf bound_ctrl:1
	s_nop 1
	v_add_f32_dpp v37, v37, v37 row_shr:4 row_mask:0xf bank_mask:0xf bound_ctrl:1
	s_nop 1
	v_add_f32_dpp v166, v37, v37 row_shr:8 row_mask:0xf bank_mask:0xf bound_ctrl:1
	v_sub_f32_e32 v167, v166, v36
	v_exp_f32_e32 v36, v85
	v_exp_f32_e32 v37, v161
	ds_bpermute_b32 v42, v9, v166 offset:28
	ds_bpermute_b32 v38, v157, v166
	v_fmamk_f32 v36, v36, 0xbf92477c, v147
	v_rcp_f32_e32 v36, v36
	v_add_f32_e32 v37, 1.0, v37
	v_rcp_f32_e32 v159, v37
	s_waitcnt lgkmcnt(1)
	v_sub_f32_e32 v32, v167, v42
	v_add_f32_dpp v37, v36, v36 row_shr:1 row_mask:0xf bank_mask:0xf bound_ctrl:1
	v_sub_f32_e32 v33, v166, v42
	v_exp_f32_e32 v166, v33
	v_add_f32_dpp v37, v37, v37 row_shr:2 row_mask:0xf bank_mask:0xf bound_ctrl:1
	v_pk_fma_f32 v[30:31], v[158:159], v[30:31], v[34:35]
	v_exp_f32_e32 v32, v32
	v_add_f32_dpp v37, v37, v37 row_shr:4 row_mask:0xf bank_mask:0xf bound_ctrl:1
	v_rcp_f32_e32 v168, v166
	s_nop 0
	v_add_f32_dpp v169, v37, v37 row_shr:8 row_mask:0xf bank_mask:0xf bound_ctrl:1
	v_sub_f32_e32 v170, v169, v36
	ds_bpermute_b32 v36, v157, v82
	v_sub_f32_e32 v82, v82, v40
	v_exp_f32_e32 v84, v82
	v_sub_f32_e32 v82, v163, v41
	v_exp_f32_e32 v161, v82
	v_sub_f32_e32 v82, v83, v41
	ds_bpermute_b32 v43, v9, v169 offset:28
	v_exp_f32_e32 v85, v82
	ds_bpermute_b32 v37, v157, v83
	v_rcp_f32_e32 v162, v84
	v_rcp_f32_e32 v163, v85
	v_fma_mix_f32 v164, v74, v84, 0 op_sel_hi:[1,0,0]
	v_fma_mix_f32 v165, v74, v85, 0 op_sel:[1,0,0] op_sel_hi:[1,0,0]
	s_waitcnt lgkmcnt(1)
	v_sub_f32_e32 v167, v169, v43
	v_exp_f32_e32 v167, v167
	v_fma_mix_f32 v82, v66, v28, 0 op_sel_hi:[1,0,0]
	v_fma_mix_f32 v83, v66, v29, 0 op_sel:[1,0,0] op_sel_hi:[1,0,0]
	v_sub_f32_e32 v33, v170, v43
	v_fma_mix_f32 v84, v67, v30, 0 op_sel_hi:[1,0,0]
	v_fma_mix_f32 v85, v67, v31, 0 op_sel:[1,0,0] op_sel_hi:[1,0,0]
	v_exp_f32_e32 v33, v33
	ds_bpermute_b32 v39, v157, v169
	v_rcp_f32_e32 v169, v167
	v_fma_mix_f32 v28, v68, v8, 0 op_sel_hi:[1,0,0]
	v_fma_mix_f32 v29, v68, v8, 0 op_sel:[1,0,0] op_sel_hi:[1,0,0]
	v_fma_mix_f32 v30, v69, v8, 0 op_sel_hi:[1,0,0]
	v_fma_mix_f32 v31, v69, v8, 0 op_sel:[1,0,0] op_sel_hi:[1,0,0]
	v_pk_mul_f32 v[34:35], v[28:29], v[160:161]
	v_pk_mul_f32 v[32:33], v[30:31], v[32:33]
	v_pk_mul_f32 v[28:29], v[86:87], v[28:29]
	v_pk_mul_f32 v[30:31], v[158:159], v[30:31]
	v_fma_mix_f32 v166, v75, v166, 0 op_sel_hi:[1,0,0]
	v_fma_mix_f32 v167, v75, v167, 0 op_sel:[1,0,0] op_sel_hi:[1,0,0]
	v_pk_mul_f32 v[28:29], v[28:29], v[162:163]
	v_pk_mul_f32 v[30:31], v[30:31], v[168:169]
	v_pk_mul_f32 v[86:87], v[82:83], v[162:163]
	v_pk_mul_f32 v[158:159], v[84:85], v[168:169]
	v_cvt_pk_f16_f32 v33, v32, v33
	v_cvt_pk_f16_f32 v32, v34, v35
	ds_write_b64 v214, v[32:33]
	v_cvt_pk_f16_f32 v33, v166, v167
	v_cvt_pk_f16_f32 v32, v164, v165
	v_cvt_pk_f16_f32 v31, v30, v31
	v_cvt_pk_f16_f32 v30, v28, v29
	v_cvt_pk_f16_f32 v29, v158, v159
	v_cvt_pk_f16_f32 v28, v86, v87
	ds_write_b64 v214, v[32:33] offset:2304
	ds_write_b64 v214, v[30:31] offset:4608
	ds_write_b64 v214, v[28:29] offset:6912
	s_waitcnt lgkmcnt(4)
	s_and_saveexec_b64 s[34:35], s[4:5]
	s_cbranch_execz .LBB0_568
	v_add_u32_e32 v28, s71, v123
	ds_write_b128 v28, v[40:43] offset:13568
	s_waitcnt lgkmcnt(0)
	ds_write_b128 v28, v[36:39] offset:13824
.LBB0_568:
	s_or_b64 exec, exec, s[34:35]
	v_exp_f32_e32 v24, v24
	v_exp_f32_e32 v20, v20
	v_exp_f32_e32 v21, v21
	v_or_b32_e32 v40, 28, v9
	v_fmamk_f32 v24, v24, 0xbf92477c, v147
	v_rcp_f32_e32 v24, v24
	v_add_f32_e32 v20, 1.0, v20
	v_rcp_f32_e32 v36, v20
	v_add_f32_e32 v21, 1.0, v21
	v_add_f32_dpp v20, v24, v24 row_shr:1 row_mask:0xf bank_mask:0xf bound_ctrl:1
	v_rcp_f32_e32 v37, v21
	v_add_u32_e32 v32, s38, v124
	v_add_f32_dpp v20, v20, v20 row_shr:2 row_mask:0xf bank_mask:0xf bound_ctrl:1
	ds_read_b128 v[28:31], v32 offset:1280
	ds_read_b128 v[32:35], v32 offset:4864
	v_add_f32_dpp v20, v20, v20 row_shr:4 row_mask:0xf bank_mask:0xf bound_ctrl:1
	v_cvt_f32_f16_sdwa v161, v70 dst_sel:DWORD dst_unused:UNUSED_PAD src0_sel:WORD_1
	v_cvt_f32_f16_e32 v160, v70
	v_add_f32_dpp v41, v20, v20 row_shr:8 row_mask:0xf bank_mask:0xf bound_ctrl:1
	v_exp_f32_e32 v20, v25
	v_sub_f32_e32 v42, v41, v24
	ds_bpermute_b32 v24, v40, v41
	s_waitcnt lgkmcnt(1)
	v_pk_fma_f32 v[28:29], v[36:37], v[28:29], v[32:33]
	v_fmamk_f32 v20, v20, 0xbf92477c, v147
	v_rcp_f32_e32 v20, v20
	v_pk_fma_f32 v[28:29], v[160:161], v[28:29], 0 op_sel_hi:[1,1,0]
	v_cvt_f32_f16_sdwa v159, v78 dst_sel:DWORD dst_unused:UNUSED_PAD src0_sel:WORD_1
	v_cvt_f32_f16_e32 v158, v78
	v_add_f32_dpp v21, v20, v20 row_shr:1 row_mask:0xf bank_mask:0xf bound_ctrl:1
	s_nop 1
	v_add_f32_dpp v21, v21, v21 row_shr:2 row_mask:0xf bank_mask:0xf bound_ctrl:1
	v_mov_b32_e32 v9, v8
	s_nop 0
	v_add_f32_dpp v21, v21, v21 row_shr:4 row_mask:0xf bank_mask:0xf bound_ctrl:1
	v_fma_mix_f32 v32, v72, v8, 0 op_sel_hi:[1,0,0]
	v_fma_mix_f32 v33, v72, v9, 0 op_sel:[1,0,0] op_sel_hi:[1,0,0]
	v_add_f32_dpp v43, v21, v21 row_shr:8 row_mask:0xf bank_mask:0xf bound_ctrl:1
	v_sub_f32_e32 v87, v43, v20
	v_exp_f32_e32 v20, v26
	v_exp_f32_e32 v21, v22
	ds_bpermute_b32 v25, v40, v43
	v_fmamk_f32 v20, v20, 0xbf92477c, v147
	v_rcp_f32_e32 v20, v20
	v_add_f32_e32 v21, 1.0, v21
	v_rcp_f32_e32 v38, v21
	s_nop 0
	v_add_f32_dpp v21, v20, v20 row_shr:1 row_mask:0xf bank_mask:0xf bound_ctrl:1
	s_nop 1
	v_add_f32_dpp v21, v21, v21 row_shr:2 row_mask:0xf bank_mask:0xf bound_ctrl:1
	s_nop 1
	v_add_f32_dpp v21, v21, v21 row_shr:4 row_mask:0xf bank_mask:0xf bound_ctrl:1
	s_nop 1
	v_add_f32_dpp v162, v21, v21 row_shr:8 row_mask:0xf bank_mask:0xf bound_ctrl:1
	v_sub_f32_e32 v163, v162, v20
	v_exp_f32_e32 v20, v27
	v_exp_f32_e32 v21, v23
	ds_bpermute_b32 v26, v40, v162
	ds_bpermute_b32 v22, v157, v162
	v_fmamk_f32 v20, v20, 0xbf92477c, v147
	v_rcp_f32_e32 v20, v20
	v_add_f32_e32 v21, 1.0, v21
	v_rcp_f32_e32 v39, v21
	s_nop 0
	v_add_f32_dpp v21, v20, v20 row_shr:1 row_mask:0xf bank_mask:0xf bound_ctrl:1
	v_pk_fma_f32 v[30:31], v[38:39], v[30:31], v[34:35]
	s_nop 0
	v_add_f32_dpp v21, v21, v21 row_shr:2 row_mask:0xf bank_mask:0xf bound_ctrl:1
	v_cvt_f32_f16_sdwa v35, v73 dst_sel:DWORD dst_unused:UNUSED_PAD src0_sel:WORD_1
	v_cvt_f32_f16_e32 v34, v73
	v_add_f32_dpp v21, v21, v21 row_shr:4 row_mask:0xf bank_mask:0xf bound_ctrl:1
	v_pk_fma_f32 v[8:9], v[34:35], v[8:9], 0 op_sel_hi:[1,1,0]
	s_nop 0
	v_add_f32_dpp v165, v21, v21 row_shr:8 row_mask:0xf bank_mask:0xf bound_ctrl:1
	ds_bpermute_b32 v27, v40, v165
	v_sub_f32_e32 v166, v165, v20
	ds_bpermute_b32 v20, v157, v41
	ds_bpermute_b32 v21, v157, v43
	ds_bpermute_b32 v23, v157, v165
	s_waitcnt lgkmcnt(5)
	v_sub_f32_e32 v157, v163, v26
	v_exp_f32_e32 v160, v157
	v_sub_f32_e32 v157, v162, v26
	v_exp_f32_e32 v162, v157
	s_waitcnt lgkmcnt(3)
	v_sub_f32_e32 v157, v166, v27
	v_sub_f32_e32 v41, v41, v24
	v_sub_f32_e32 v43, v43, v25
	v_exp_f32_e32 v161, v157
	v_sub_f32_e32 v157, v165, v27
	v_sub_f32_e32 v40, v42, v24
	v_exp_f32_e32 v42, v41
	v_exp_f32_e32 v43, v43
	v_exp_f32_e32 v163, v157
	v_sub_f32_e32 v41, v87, v25
	v_exp_f32_e32 v40, v40
	v_exp_f32_e32 v41, v41
	v_rcp_f32_e32 v86, v42
	v_rcp_f32_e32 v87, v43
	v_rcp_f32_e32 v164, v162
	v_rcp_f32_e32 v165, v163
	v_pk_fma_f32 v[42:43], v[158:159], v[42:43], 0 op_sel_hi:[1,1,0]
	v_fma_mix_f32 v158, v79, v162, 0 op_sel_hi:[1,0,0]
	v_fma_mix_f32 v159, v79, v163, 0 op_sel:[1,0,0] op_sel_hi:[1,0,0]
	v_pk_mul_f32 v[34:35], v[32:33], v[40:41]
	v_pk_mul_f32 v[40:41], v[8:9], v[160:161]
	v_pk_mul_f32 v[32:33], v[36:37], v[32:33]
	v_pk_mul_f32 v[8:9], v[38:39], v[8:9]
	v_fma_mix_f32 v30, v71, v30, 0 op_sel_hi:[1,0,0]
	v_fma_mix_f32 v31, v71, v31, 0 op_sel:[1,0,0] op_sel_hi:[1,0,0]
	v_pk_mul_f32 v[32:33], v[32:33], v[86:87]
	v_pk_mul_f32 v[8:9], v[8:9], v[164:165]
	v_pk_mul_f32 v[36:37], v[28:29], v[86:87]
	v_pk_mul_f32 v[38:39], v[30:31], v[164:165]
	v_add_u32_e32 v86, s71, v114
	v_cvt_pk_f16_f32 v9, v8, v9
	v_cvt_pk_f16_f32 v8, v32, v33
	v_cvt_pk_f16_f32 v41, v40, v41
	v_cvt_pk_f16_f32 v40, v34, v35
	v_cvt_pk_f16_f32 v35, v158, v159
	v_cvt_pk_f16_f32 v34, v42, v43
	ds_write_b64 v86, v[8:9] offset:4608
	v_cvt_pk_f16_f32 v9, v38, v39
	v_cvt_pk_f16_f32 v8, v36, v37
	ds_write_b64 v86, v[40:41]
	ds_write_b64 v86, v[34:35] offset:2304
	ds_write_b64 v86, v[8:9] offset:6912
	s_waitcnt lgkmcnt(4)
	s_and_saveexec_b64 s[34:35], s[4:5]
	s_cbranch_execz .LBB0_570
	v_add_u32_e32 v8, s71, v124
	ds_write_b128 v8, v[24:27] offset:13568
	ds_write_b128 v8, v[20:23] offset:13824
